# w15: w9 + gla_seq step loop: LDS operand reads hoisted into two batches with counted lgkmcnt waits (12 for the output chain, 8 for the state update)
# baseline (speedup 1.0000x reference)
; #define LAS __attribute__((address_space(3)))
; #define MFMA16(a, b, c) __builtin_amdgcn_mfma_f32_16x16x32_bf16((a), (b), (c), 0, 0, 0)
; DI void gla_seq_step(Frame& F, const GlaOps& cur, const GlaOps& nxt, f32x4 (&acc)[4], LAS bf16* ST, int b, int h, int vs, int c, int w, int r16, int kq, int tid) {
;     const int ti = w >> 1, tp = w & 1;
;     const LAS bf16* Sc = ST + (c & 1) * 64 * 136; LAS bf16* Sn = ST + ((c & 1) ^ 1) * 64 * 136;
;     const LAS bf16* Vc = (const LAS bf16*)((LAS unsigned char*)ST + 69632) + (c & 1) * 64 * 72; LAS bf16* Vn = (LAS bf16*)((LAS unsigned char*)ST + 69632) + ((c & 1) ^ 1) * 64 * 72;
;     *(LAS u32x4*)(Vn + (tid >> 3) * 72 + (tid & 7) * 8) = nxt.vs;
;     f32x4 o0 = {0.f, 0.f, 0.f, 0.f}, o1 = o0;
;     { const LAS bf16* vp = Vc + (32 * tp + r16) * 72 + 8 * kq;
;       o0 = MFMA16(cur.aA0, *(const LAS bf16x8*)vp, o0); o0 = MFMA16(cur.aA1, *(const LAS bf16x8*)(vp + 32), o0);
;       o1 = MFMA16(cur.aA0, *(const LAS bf16x8*)(vp + 16 * 72), o1); o1 = MFMA16(cur.aA1, *(const LAS bf16x8*)(vp + 16 * 72 + 32), o1); }
;     { const LAS bf16* sp = Sc + (32 * tp + r16) * 136 + 8 * kq;
;       o0 = MFMA16(cur.aQ0, *(const LAS bf16x8*)sp, o0); o0 = MFMA16(cur.aQ1, *(const LAS bf16x8*)(sp + 32), o0); o0 = MFMA16(cur.aQ2, *(const LAS bf16x8*)(sp + 64), o0); o0 = MFMA16(cur.aQ3, *(const LAS bf16x8*)(sp + 96), o0);
;       sp += 16 * 136;
;       o1 = MFMA16(cur.aQ0, *(const LAS bf16x8*)sp, o1); o1 = MFMA16(cur.aQ1, *(const LAS bf16x8*)(sp + 32), o1); o1 = MFMA16(cur.aQ2, *(const LAS bf16x8*)(sp + 64), o1); o1 = MFMA16(cur.aQ3, *(const LAS bf16x8*)(sp + 96), o1); }
;     { LAS float* ob = (LAS float*)(ST + 2 * 64 * 136) + (c & 1) * 64 * 68 + (16 * ti + 4 * kq) * 68 + 32 * tp + r16;
; #pragma unroll
;       for (int i = 0; i < 4; ++i) { ob[i * 68] = o0[i]; ob[i * 68 + 16] = o1[i]; } }
; #pragma unroll
;     for (int tv = 0; tv < 4; ++tv) { const LAS bf16* vp = Vc + (16 * tv + r16) * 72 + 8 * kq;
;         acc[tv] = MFMA16(*(const LAS bf16x8*)vp, cur.bK0, acc[tv]); acc[tv] = MFMA16(*(const LAS bf16x8*)(vp + 32), cur.bK1, acc[tv]); acc[tv] = acc[tv] * cur.dD; }
; #pragma unroll
;     for (int tv = 0; tv < 4; ++tv)
; #pragma unroll
;         for (int i = 0; i < 4; ++i) Sn[(16 * tv + 4 * kq + i) * 136 + 16 * w + r16] = (bf16)(pk2(acc[tv][i], 0.f) & 0xffffu);
;     __syncthreads();
; }
.LBB0_1226:
	s_add_i32 s21, s23, 3
	s_and_b32 s39, s21, 1
	s_lshl_b32 s38, s39, 6
	s_mul_i32 s40, s39, 0x4400
	s_xor_b32 s41, s38, 64
	s_mulk_i32 s39, 0x2400
	s_mul_i32 s38, s41, 0x110
	s_add_i32 s39, s31, s39
	s_mulk_i32 s41, 0x90
	v_add_u32_e32 v181, s41, v172
	v_add_u32_e32 v135, s39, v174
	s_waitcnt vmcnt(11)
	ds_write_b128 v181, v[70:73]
	v_add_u32_e32 v180, v135, v173
	v_add_u32_e32 v178, s40, v170
	ds_read_b128 v[188:191], v180
	ds_read_b128 v[192:195], v180 offset:64
	ds_read_b128 v[196:199], v180 offset:2304
	ds_read_b128 v[200:203], v180 offset:2368
	ds_read_b128 v[204:207], v178
	ds_read_b128 v[208:211], v178 offset:64
	ds_read_b128 v[212:215], v178 offset:128
	ds_read_b128 v[216:219], v178 offset:192
	ds_read_b128 v[220:223], v178 offset:4352
	ds_read_b128 v[224:227], v178 offset:4416
	ds_read_b128 v[228:231], v178 offset:4480
	ds_read_b128 v[232:235], v178 offset:4544
	s_nop 0
	s_nop 0
	s_nop 0
	s_waitcnt lgkmcnt(11)
	v_mfma_f32_16x16x32_bf16 v[70:73], v[62:65], v[188:191], 0
	s_nop 0
	v_add_u32_e32 v135, v135, v159
	v_add_u32_e32 v177, s38, v141
	s_waitcnt lgkmcnt(10)
	v_mfma_f32_16x16x32_bf16 v[70:73], v[58:61], v[192:195], v[70:73]
	s_nop 0
	s_mov_b32 s38, 0x59e06000
	v_lshl_add_u64 v[150:151], v[150:151], 0, s[6:7]
	s_waitcnt lgkmcnt(9)
	v_mfma_f32_16x16x32_bf16 v[62:65], v[62:65], v[196:199], 0
	s_nop 0
	v_lshl_add_u64 v[152:153], v[152:153], 0, s[6:7]
	s_waitcnt lgkmcnt(8)
	v_mfma_f32_16x16x32_bf16 v[58:61], v[58:61], v[200:203], v[62:65]
	s_nop 3
	s_nop 0
	s_waitcnt lgkmcnt(7)
	v_mfma_f32_16x16x32_bf16 v[62:65], v[54:57], v[204:207], v[70:73]
	s_nop 2
	s_nop 0
	s_waitcnt lgkmcnt(6)
	v_mfma_f32_16x16x32_bf16 v[62:65], v[50:53], v[208:211], v[62:65]
	s_nop 0
	s_waitcnt lgkmcnt(5)
	v_mfma_f32_16x16x32_bf16 v[62:65], v[46:49], v[212:215], v[62:65]
	s_nop 0
	s_waitcnt lgkmcnt(4)
	v_mfma_f32_16x16x32_bf16 v[62:65], v[38:41], v[216:219], v[62:65]
	ds_read_b128 v[188:191], v135
	ds_read_b128 v[192:195], v135 offset:64
	ds_read_b128 v[196:199], v135 offset:2304
	ds_read_b128 v[200:203], v135 offset:2368
	ds_read_b128 v[204:207], v135 offset:4608
	ds_read_b128 v[208:211], v135 offset:4672
	ds_read_b128 v[212:215], v135 offset:6912
	ds_read_b128 v[216:219], v135 offset:6976
	s_nop 0
	s_waitcnt lgkmcnt(11)
	v_mfma_f32_16x16x32_bf16 v[54:57], v[54:57], v[220:223], v[58:61]
	s_nop 2
	s_nop 0
	s_waitcnt lgkmcnt(10)
	v_mfma_f32_16x16x32_bf16 v[50:53], v[50:53], v[224:227], v[54:57]
	s_nop 2
	s_nop 0
	s_waitcnt lgkmcnt(9)
	v_mfma_f32_16x16x32_bf16 v[46:49], v[46:49], v[228:231], v[50:53]
	s_nop 2
	s_nop 0
	s_waitcnt lgkmcnt(8)
	v_mfma_f32_16x16x32_bf16 v[38:41], v[38:41], v[232:235], v[46:49]
	s_nop 2
	v_add_u32_e32 v46, s40, v171
	v_add_u32_e32 v179, 0x8800, v46
	s_nop 2
	ds_write2_b32 v179, v62, v38 offset1:16
	ds_write2_b32 v179, v63, v39 offset0:68 offset1:84
	ds_write2_b32 v179, v64, v40 offset0:136 offset1:152
	ds_write2_b32 v179, v65, v41 offset0:204 offset1:220
	s_nop 0
	s_nop 0
	s_waitcnt lgkmcnt(11)
	v_mfma_f32_16x16x32_bf16 v[38:41], v[188:191], v[14:17], v[110:113]
	s_waitcnt lgkmcnt(10)
	v_mfma_f32_16x16x32_bf16 v[38:41], v[192:195], v[6:9], v[38:41]
	s_nop 0
	s_nop 6
	v_pk_mul_f32 v[112:113], v[140:141], v[40:41] op_sel_hi:[0,1]
	v_pk_mul_f32 v[110:111], v[140:141], v[38:39] op_sel_hi:[0,1]
	s_nop 0
	s_waitcnt lgkmcnt(9)
	v_mfma_f32_16x16x32_bf16 v[38:41], v[196:199], v[14:17], v[114:117]
	s_waitcnt lgkmcnt(8)
	v_mfma_f32_16x16x32_bf16 v[38:41], v[200:203], v[6:9], v[38:41]
	s_nop 0
	s_nop 6
	v_pk_mul_f32 v[116:117], v[140:141], v[40:41] op_sel_hi:[0,1]
	v_pk_mul_f32 v[114:115], v[140:141], v[38:39] op_sel_hi:[0,1]
	s_nop 0
	s_waitcnt lgkmcnt(7)
	v_mfma_f32_16x16x32_bf16 v[38:41], v[204:207], v[14:17], v[106:109]
	s_nop 2
	v_lshl_add_u64 v[106:107], v[142:143], 0, s[4:5]
	v_lshlrev_b64 v[106:107], 12, v[106:107]
	v_lshl_add_u64 v[182:183], v[144:145], 0, v[106:107]
	s_waitcnt lgkmcnt(6)
	v_mfma_f32_16x16x32_bf16 v[38:41], v[208:211], v[6:9], v[38:41]
	s_nop 7
	v_pk_mul_f32 v[72:73], v[140:141], v[40:41] op_sel_hi:[0,1]
	v_pk_mul_f32 v[70:71], v[140:141], v[38:39] op_sel_hi:[0,1]
	s_nop 0
	s_waitcnt lgkmcnt(5)
	v_mfma_f32_16x16x32_bf16 v[14:17], v[212:215], v[14:17], v[102:105]
	s_nop 0
	s_waitcnt lgkmcnt(4)
	v_mfma_f32_16x16x32_bf16 v[6:9], v[216:219], v[6:9], v[14:17]
	s_nop 7
	v_pk_mul_f32 v[122:123], v[140:141], v[6:7] op_sel_hi:[0,1]
	v_cvt_pk_bf16_f32 v6, v110, s0
	ds_write_b16 v177, v6
	v_cvt_pk_bf16_f32 v6, v111, s0
	ds_write_b16 v177, v6 offset:272
	v_cvt_pk_bf16_f32 v6, v112, s0
	ds_write_b16 v177, v6 offset:544
	v_cvt_pk_bf16_f32 v6, v113, s0
	ds_write_b16 v177, v6 offset:816
	v_cvt_pk_bf16_f32 v6, v114, s0
	ds_write_b16 v177, v6 offset:4352
	v_cvt_pk_bf16_f32 v6, v115, s0
	ds_write_b16 v177, v6 offset:4624
	v_cvt_pk_bf16_f32 v6, v116, s0
	ds_write_b16 v177, v6 offset:4896
	v_cvt_pk_bf16_f32 v6, v117, s0
	ds_write_b16 v177, v6 offset:5168
	v_cvt_pk_bf16_f32 v6, v70, s0
	ds_write_b16 v177, v6 offset:8704
	v_cvt_pk_bf16_f32 v6, v71, s0
	ds_write_b16 v177, v6 offset:8976
	v_cvt_pk_bf16_f32 v6, v72, s0
	ds_write_b16 v177, v6 offset:9248
	v_cvt_pk_bf16_f32 v6, v73, s0
	ds_write_b16 v177, v6 offset:9520
	v_cvt_pk_bf16_f32 v6, v122, s0
	v_pk_mul_f32 v[124:125], v[140:141], v[8:9] op_sel_hi:[0,1]
	ds_write_b16 v177, v6 offset:13056
	v_cvt_pk_bf16_f32 v6, v123, s0
	ds_write_b16 v177, v6 offset:13328
	v_cvt_pk_bf16_f32 v6, v124, s0
	ds_write_b16 v177, v6 offset:13600
	v_cvt_pk_bf16_f32 v6, v125, s0
	ds_write_b16 v177, v6 offset:13872
	v_add_co_u32_e32 v6, vcc, s38, v164
	s_mov_b32 s38, 0x58e0c000
	s_nop 0
	v_addc_co_u32_e32 v7, vcc, 0, v165, vcc
	s_waitcnt lgkmcnt(0)
	s_barrier
; #define LAS __attribute__((address_space(3)))
; DI unsigned pk2(float lo, float hi) { f32x2 v = {lo, hi}; bf16x2_t b = __builtin_convertvector(v, bf16x2_t); return __builtin_bit_cast(unsigned, b); }
; DI void gla_seq_step(Frame& F, const GlaOps& cur, const GlaOps& nxt, f32x4 (&acc)[4], LAS bf16* ST, int b, int h, int vs, int c, int w, int r16, int kq, int tid) {
;     const int ti = w >> 1, tp = w & 1;
;     const LAS bf16* Sc = ST + (c & 1) * 64 * 136; LAS bf16* Sn = ST + ((c & 1) ^ 1) * 64 * 136;
;     const LAS bf16* Vc = (const LAS bf16*)((LAS unsigned char*)ST + 69632) + (c & 1) * 64 * 72; LAS bf16* Vn = (LAS bf16*)((LAS unsigned char*)ST + 69632) + ((c & 1) ^ 1) * 64 * 72;
;     *(LAS u32x4*)(Vn + (tid >> 3) * 72 + (tid & 7) * 8) = nxt.vs;
;     f32x4 o0 = {0.f, 0.f, 0.f, 0.f}, o1 = o0;
;     { const LAS bf16* vp = Vc + (32 * tp + r16) * 72 + 8 * kq;
;       o0 = MFMA16(cur.aA0, *(const LAS bf16x8*)vp, o0); o0 = MFMA16(cur.aA1, *(const LAS bf16x8*)(vp + 32), o0);
;       o1 = MFMA16(cur.aA0, *(const LAS bf16x8*)(vp + 16 * 72), o1); o1 = MFMA16(cur.aA1, *(const LAS bf16x8*)(vp + 16 * 72 + 32), o1); }
;     { const LAS bf16* sp = Sc + (32 * tp + r16) * 136 + 8 * kq;
;       o0 = MFMA16(cur.aQ0, *(const LAS bf16x8*)sp, o0); o0 = MFMA16(cur.aQ1, *(const LAS bf16x8*)(sp + 32), o0); o0 = MFMA16(cur.aQ2, *(const LAS bf16x8*)(sp + 64), o0); o0 = MFMA16(cur.aQ3, *(const LAS bf16x8*)(sp + 96), o0);
;       sp += 16 * 136;
;       o1 = MFMA16(cur.aQ0, *(const LAS bf16x8*)sp, o1); o1 = MFMA16(cur.aQ1, *(const LAS bf16x8*)(sp + 32), o1); o1 = MFMA16(cur.aQ2, *(const LAS bf16x8*)(sp + 64), o1); o1 = MFMA16(cur.aQ3, *(const LAS bf16x8*)(sp + 96), o1); }
;     { LAS float* ob = (LAS float*)(ST + 2 * 64 * 136) + (c & 1) * 64 * 68 + (16 * ti + 4 * kq) * 68 + 32 * tp + r16;
; #pragma unroll
;       for (int i = 0; i < 4; ++i) { ob[i * 68] = o0[i]; ob[i * 68 + 16] = o1[i]; } }
; #pragma unroll
;     for (int tv = 0; tv < 4; ++tv) { const LAS bf16* vp = Vc + (16 * tv + r16) * 72 + 8 * kq;
;         acc[tv] = MFMA16(*(const LAS bf16x8*)vp, cur.bK0, acc[tv]); acc[tv] = MFMA16(*(const LAS bf16x8*)(vp + 32), cur.bK1, acc[tv]); acc[tv] = acc[tv] * cur.dD; }
; #pragma unroll
;     for (int tv = 0; tv < 4; ++tv)
; #pragma unroll
;         for (int i = 0; i < 4; ++i) Sn[(16 * tv + 4 * kq + i) * 136 + 16 * w + r16] = (bf16)(pk2(acc[tv][i], 0.f) & 0xffffu);
	global_load_dwordx4 v[62:65], v[6:7], off
	global_load_dwordx4 v[58:61], v[6:7], off offset:64
	v_add_co_u32_e32 v6, vcc, s38, v162
	s_mov_b32 s38, 0x57e0c000
	s_nop 0
	v_addc_co_u32_e32 v7, vcc, 0, v163, vcc
	v_add_co_u32_e32 v38, vcc, s38, v160
	s_mov_b32 s38, 0x5a618000
	s_nop 0
	v_addc_co_u32_e32 v39, vcc, 0, v161, vcc
	v_add_co_u32_e32 v102, vcc, s38, v166
	s_and_b32 s38, s4, 64
	s_mulk_i32 s38, 0x110
	v_addc_co_u32_e32 v103, vcc, 0, v167, vcc
	v_add_u32_e32 v184, s38, v127
	global_load_dwordx4 v[14:17], v[6:7], off
	s_nop 0
	global_load_dwordx4 v[6:9], v[6:7], off offset:64
	s_nop 0
	global_load_dwordx4 v[54:57], v[38:39], off
	global_load_dwordx4 v[50:53], v[38:39], off offset:64
	global_load_dwordx4 v[46:49], v[38:39], off offset:128
	s_nop 0
	global_load_dwordx4 v[38:41], v[38:39], off offset:192
	s_nop 0
	global_load_dwordx4 v[102:105], v[102:103], off
	s_nop 0
	global_load_dword v140, v[168:169], off
	ds_read_b128 v[106:109], v184 offset:34816
	s_add_i32 s4, s23, 4
	s_and_b32 s23, s4, 1
	s_lshl_b32 s4, s23, 6
	s_mul_i32 s38, s23, 0x4400
	s_waitcnt lgkmcnt(0)
	global_store_dwordx4 v[182:183], v[106:109], off
	ds_read_b128 v[106:109], v184 offset:34944
	s_xor_b32 s39, s4, 64
	s_mulk_i32 s23, 0x2400
	s_mul_i32 s4, s39, 0x110
	s_add_i32 s23, s31, s23
	s_mulk_i32 s39, 0x90
	s_waitcnt lgkmcnt(0)
	global_store_dwordx4 v[182:183], v[106:109], off offset:128
	v_add_u32_e32 v182, s23, v174
	v_add_u32_e32 v183, v182, v173
	v_add_u32_e32 v106, s39, v172
	s_waitcnt vmcnt(13)
	ds_write_b128 v106, v[118:121]
	v_add_u32_e32 v240, s38, v170
	ds_read_b128 v[188:191], v183
	ds_read_b128 v[192:195], v183 offset:64
	ds_read_b128 v[196:199], v183 offset:2304
	ds_read_b128 v[200:203], v183 offset:2368
	ds_read_b128 v[204:207], v240
	ds_read_b128 v[208:211], v240 offset:64
	ds_read_b128 v[212:215], v240 offset:128
	ds_read_b128 v[216:219], v240 offset:192
	ds_read_b128 v[220:223], v240 offset:4352
	ds_read_b128 v[224:227], v240 offset:4416
	ds_read_b128 v[228:231], v240 offset:4480
	ds_read_b128 v[232:235], v240 offset:4544
	s_nop 0
	s_nop 0
	s_waitcnt lgkmcnt(11)
	v_mfma_f32_16x16x32_bf16 v[106:109], v[42:45], v[188:191], 0
	s_waitcnt lgkmcnt(10)
	v_mfma_f32_16x16x32_bf16 v[106:109], v[34:37], v[192:195], v[106:109]
	s_nop 0
	s_waitcnt lgkmcnt(9)
	v_mfma_f32_16x16x32_bf16 v[42:45], v[42:45], v[196:199], 0
	s_nop 0
	s_waitcnt lgkmcnt(8)
	v_mfma_f32_16x16x32_bf16 v[34:37], v[34:37], v[200:203], v[42:45]
	s_nop 0
	s_nop 3
	s_nop 0
	s_waitcnt lgkmcnt(7)
	v_mfma_f32_16x16x32_bf16 v[42:45], v[30:33], v[204:207], v[106:109]
	s_nop 2
	s_nop 0
	s_waitcnt lgkmcnt(6)
	v_mfma_f32_16x16x32_bf16 v[42:45], v[26:29], v[208:211], v[42:45]
	s_nop 0
	s_waitcnt lgkmcnt(5)
	v_mfma_f32_16x16x32_bf16 v[42:45], v[22:25], v[212:215], v[42:45]
	s_nop 0
	s_waitcnt lgkmcnt(4)
	v_mfma_f32_16x16x32_bf16 v[42:45], v[18:21], v[216:219], v[42:45]
	v_add_u32_e32 v241, v182, v159
	ds_read_b128 v[188:191], v241
	ds_read_b128 v[192:195], v241 offset:64
	ds_read_b128 v[196:199], v241 offset:2304
	ds_read_b128 v[200:203], v241 offset:2368
	ds_read_b128 v[204:207], v241 offset:4608
	ds_read_b128 v[208:211], v241 offset:4672
	ds_read_b128 v[212:215], v241 offset:6912
	ds_read_b128 v[216:219], v241 offset:6976
	s_nop 0
	s_waitcnt lgkmcnt(11)
	v_mfma_f32_16x16x32_bf16 v[30:33], v[30:33], v[220:223], v[34:37]
	s_nop 2
	s_nop 0
	s_waitcnt lgkmcnt(10)
	v_mfma_f32_16x16x32_bf16 v[26:29], v[26:29], v[224:227], v[30:33]
	s_nop 2
	s_nop 0
	s_waitcnt lgkmcnt(9)
	v_mfma_f32_16x16x32_bf16 v[22:25], v[22:25], v[228:231], v[26:29]
	s_nop 2
	s_nop 0
	s_waitcnt lgkmcnt(8)
	v_mfma_f32_16x16x32_bf16 v[18:21], v[18:21], v[232:235], v[22:25]
	s_nop 2
	v_add_u32_e32 v22, s38, v171
	v_add_u32_e32 v22, 0x8800, v22
	s_nop 2
	ds_write2_b32 v22, v42, v18 offset1:16
	ds_write2_b32 v22, v43, v19 offset0:68 offset1:84
	ds_write2_b32 v22, v44, v20 offset0:136 offset1:152
	ds_write2_b32 v22, v45, v21 offset0:204 offset1:220
	s_nop 0
	s_nop 0
	s_nop 0
	s_waitcnt lgkmcnt(11)
	v_mfma_f32_16x16x32_bf16 v[18:21], v[188:191], v[10:13], v[110:113]
	s_mov_b64 s[38:39], 0x18000
	v_lshl_add_u64 v[146:147], v[146:147], 0, s[38:39]
	s_mov_b64 s[38:39], 0x6000
	s_waitcnt lgkmcnt(10)
	v_mfma_f32_16x16x32_bf16 v[18:21], v[192:195], v[2:5], v[18:21]
	s_nop 0
	v_lshl_add_u64 v[148:149], v[148:149], 0, s[38:39]
	s_mov_b64 s[38:39], 0xc0000
	s_nop 4
	v_pk_mul_f32 v[112:113], v[138:139], v[20:21] op_sel_hi:[0,1]
	v_pk_mul_f32 v[110:111], v[138:139], v[18:19] op_sel_hi:[0,1]
	s_nop 0
	s_waitcnt lgkmcnt(9)
	v_mfma_f32_16x16x32_bf16 v[18:21], v[196:199], v[10:13], v[114:117]
	s_waitcnt lgkmcnt(8)
	v_mfma_f32_16x16x32_bf16 v[18:21], v[200:203], v[2:5], v[18:21]
	s_nop 0
	s_nop 6
	v_pk_mul_f32 v[116:117], v[138:139], v[20:21] op_sel_hi:[0,1]
	v_pk_mul_f32 v[114:115], v[138:139], v[18:19] op_sel_hi:[0,1]
	s_nop 0
	s_waitcnt lgkmcnt(7)
	v_mfma_f32_16x16x32_bf16 v[18:21], v[204:207], v[10:13], v[70:73]
	s_waitcnt lgkmcnt(6)
	v_mfma_f32_16x16x32_bf16 v[18:21], v[208:211], v[2:5], v[18:21]
	s_nop 7
	v_pk_mul_f32 v[108:109], v[138:139], v[20:21] op_sel_hi:[0,1]
	v_pk_mul_f32 v[106:107], v[138:139], v[18:19] op_sel_hi:[0,1]
	s_nop 0
	s_waitcnt lgkmcnt(5)
	v_mfma_f32_16x16x32_bf16 v[10:13], v[212:215], v[10:13], v[122:125]
	s_nop 0
	s_waitcnt lgkmcnt(4)
	v_mfma_f32_16x16x32_bf16 v[2:5], v[216:219], v[2:5], v[10:13]
	s_nop 7
	v_pk_mul_f32 v[118:119], v[138:139], v[2:3] op_sel_hi:[0,1]
	v_cvt_pk_bf16_f32 v2, v110, s0
	v_add_u32_e32 v3, s4, v141
	ds_write_b16 v3, v2
	v_cvt_pk_bf16_f32 v2, v111, s0
	ds_write_b16 v3, v2 offset:272
	v_cvt_pk_bf16_f32 v2, v112, s0
	ds_write_b16 v3, v2 offset:544
	v_cvt_pk_bf16_f32 v2, v113, s0
	ds_write_b16 v3, v2 offset:816
	v_cvt_pk_bf16_f32 v2, v114, s0
	ds_write_b16 v3, v2 offset:4352
	v_cvt_pk_bf16_f32 v2, v115, s0
	ds_write_b16 v3, v2 offset:4624
	v_cvt_pk_bf16_f32 v2, v116, s0
	ds_write_b16 v3, v2 offset:4896
	v_cvt_pk_bf16_f32 v2, v117, s0
	ds_write_b16 v3, v2 offset:5168
	v_cvt_pk_bf16_f32 v2, v106, s0
	ds_write_b16 v3, v2 offset:8704
	v_cvt_pk_bf16_f32 v2, v107, s0
	ds_write_b16 v3, v2 offset:8976
	v_cvt_pk_bf16_f32 v2, v108, s0
	ds_write_b16 v3, v2 offset:9248
	v_cvt_pk_bf16_f32 v2, v109, s0
	ds_write_b16 v3, v2 offset:9520
	v_cvt_pk_bf16_f32 v2, v118, s0
	v_pk_mul_f32 v[120:121], v[138:139], v[4:5] op_sel_hi:[0,1]
	ds_write_b16 v3, v2 offset:13056
	v_cvt_pk_bf16_f32 v2, v119, s0
	ds_write_b16 v3, v2 offset:13328
	v_cvt_pk_bf16_f32 v2, v120, s0
	ds_write_b16 v3, v2 offset:13600
	v_cvt_pk_bf16_f32 v2, v121, s0
	s_mov_b32 s4, 0x59e08000
	ds_write_b16 v3, v2 offset:13872
	v_add_co_u32_e32 v2, vcc, s4, v164
	s_mov_b32 s4, 0x58e10000
	s_nop 0
	v_addc_co_u32_e32 v3, vcc, 0, v165, vcc
	s_waitcnt lgkmcnt(0)
	s_barrier
; #define LAS __attribute__((address_space(3)))
; DI unsigned pk2(float lo, float hi) { f32x2 v = {lo, hi}; bf16x2_t b = __builtin_convertvector(v, bf16x2_t); return __builtin_bit_cast(unsigned, b); }
; DI void gla_seq_step(Frame& F, const GlaOps& cur, const GlaOps& nxt, f32x4 (&acc)[4], LAS bf16* ST, int b, int h, int vs, int c, int w, int r16, int kq, int tid) {
;     const int ti = w >> 1, tp = w & 1;
;     const LAS bf16* Sc = ST + (c & 1) * 64 * 136; LAS bf16* Sn = ST + ((c & 1) ^ 1) * 64 * 136;
;     const LAS bf16* Vc = (const LAS bf16*)((LAS unsigned char*)ST + 69632) + (c & 1) * 64 * 72; LAS bf16* Vn = (LAS bf16*)((LAS unsigned char*)ST + 69632) + ((c & 1) ^ 1) * 64 * 72;
;     *(LAS u32x4*)(Vn + (tid >> 3) * 72 + (tid & 7) * 8) = nxt.vs;
;     f32x4 o0 = {0.f, 0.f, 0.f, 0.f}, o1 = o0;
;     { const LAS bf16* vp = Vc + (32 * tp + r16) * 72 + 8 * kq;
;       o0 = MFMA16(cur.aA0, *(const LAS bf16x8*)vp, o0); o0 = MFMA16(cur.aA1, *(const LAS bf16x8*)(vp + 32), o0);
;       o1 = MFMA16(cur.aA0, *(const LAS bf16x8*)(vp + 16 * 72), o1); o1 = MFMA16(cur.aA1, *(const LAS bf16x8*)(vp + 16 * 72 + 32), o1); }
;     { const LAS bf16* sp = Sc + (32 * tp + r16) * 136 + 8 * kq;
;       o0 = MFMA16(cur.aQ0, *(const LAS bf16x8*)sp, o0); o0 = MFMA16(cur.aQ1, *(const LAS bf16x8*)(sp + 32), o0); o0 = MFMA16(cur.aQ2, *(const LAS bf16x8*)(sp + 64), o0); o0 = MFMA16(cur.aQ3, *(const LAS bf16x8*)(sp + 96), o0);
;       sp += 16 * 136;
;       o1 = MFMA16(cur.aQ0, *(const LAS bf16x8*)sp, o1); o1 = MFMA16(cur.aQ1, *(const LAS bf16x8*)(sp + 32), o1); o1 = MFMA16(cur.aQ2, *(const LAS bf16x8*)(sp + 64), o1); o1 = MFMA16(cur.aQ3, *(const LAS bf16x8*)(sp + 96), o1); }
;     { LAS float* ob = (LAS float*)(ST + 2 * 64 * 136) + (c & 1) * 64 * 68 + (16 * ti + 4 * kq) * 68 + 32 * tp + r16;
; #pragma unroll
;       for (int i = 0; i < 4; ++i) { ob[i * 68] = o0[i]; ob[i * 68 + 16] = o1[i]; } }
; #pragma unroll
;     for (int tv = 0; tv < 4; ++tv) { const LAS bf16* vp = Vc + (16 * tv + r16) * 72 + 8 * kq;
;         acc[tv] = MFMA16(*(const LAS bf16x8*)vp, cur.bK0, acc[tv]); acc[tv] = MFMA16(*(const LAS bf16x8*)(vp + 32), cur.bK1, acc[tv]); acc[tv] = acc[tv] * cur.dD; }
; #pragma unroll
;     for (int tv = 0; tv < 4; ++tv)
; #pragma unroll
;         for (int i = 0; i < 4; ++i) Sn[(16 * tv + 4 * kq + i) * 136 + 16 * w + r16] = (bf16)(pk2(acc[tv][i], 0.f) & 0xffffu);
	global_load_dwordx4 v[42:45], v[2:3], off
	global_load_dwordx4 v[34:37], v[2:3], off offset:64
	v_add_co_u32_e32 v2, vcc, s4, v162
	s_mov_b32 s4, 0x57e10000
	s_nop 0
	v_addc_co_u32_e32 v3, vcc, 0, v163, vcc
	v_add_co_u32_e32 v18, vcc, s4, v160
	s_mov_b32 s4, 0x5a620000
	s_nop 0
	v_addc_co_u32_e32 v19, vcc, 0, v161, vcc
	v_add_co_u32_e32 v70, vcc, s4, v166
	s_add_i32 s4, s20, 64
	s_and_b32 s4, s4, 64
	s_mulk_i32 s4, 0x110
	v_addc_co_u32_e32 v71, vcc, 0, v167, vcc
	v_add_u32_e32 v162, s4, v127
	global_load_dwordx4 v[10:13], v[2:3], off
	s_nop 0
	global_load_dwordx4 v[2:5], v[2:3], off offset:64
	s_nop 0
	global_load_dwordx4 v[30:33], v[18:19], off
	global_load_dwordx4 v[26:29], v[18:19], off offset:64
	global_load_dwordx4 v[22:25], v[18:19], off offset:128
	s_nop 0
	global_load_dwordx4 v[18:21], v[18:19], off offset:192
	s_nop 0
	global_load_dwordx4 v[70:73], v[70:71], off
	s_nop 0
	global_load_dword v138, v[168:169], off offset:512
	ds_read_b128 v[122:125], v162 offset:34816
	v_lshl_add_u64 v[160:161], s[46:47], 0, v[154:155]
	s_mov_b32 s4, 0x34040000
	v_add_co_u32_e32 v160, vcc, s4, v160
	s_addk_i32 s20, 0xc0
	s_nop 0
	v_addc_co_u32_e32 v161, vcc, 0, v161, vcc
	s_waitcnt lgkmcnt(0)
	global_store_dwordx4 v[160:161], v[122:125], off
	ds_read_b128 v[122:125], v162 offset:34944
	s_waitcnt vmcnt(14)
	ds_write_b128 v181, v[102:105]
	ds_read_b128 v[188:191], v180
	ds_read_b128 v[192:195], v180 offset:64
	ds_read_b128 v[196:199], v180 offset:2304
	ds_read_b128 v[200:203], v180 offset:2368
	ds_read_b128 v[204:207], v178
	ds_read_b128 v[208:211], v178 offset:64
	ds_read_b128 v[212:215], v178 offset:128
	ds_read_b128 v[216:219], v178 offset:192
	ds_read_b128 v[220:223], v178 offset:4352
	ds_read_b128 v[224:227], v178 offset:4416
	ds_read_b128 v[228:231], v178 offset:4480
	ds_read_b128 v[232:235], v178 offset:4544
	s_nop 0
	v_lshl_add_u64 v[154:155], v[154:155], 0, s[38:39]
	s_mov_b64 s[38:39], 0x600
	s_waitcnt lgkmcnt(13)
	global_store_dwordx4 v[160:161], v[122:125], off offset:128
	s_nop 0
	s_waitcnt lgkmcnt(11)
	v_mfma_f32_16x16x32_bf16 v[102:105], v[98:101], v[188:191], 0
	v_lshl_add_u64 v[156:157], v[156:157], 0, s[38:39]
	s_cmp_lt_u32 s21, 27
	s_waitcnt lgkmcnt(10)
	v_mfma_f32_16x16x32_bf16 v[102:105], v[94:97], v[192:195], v[102:105]
	s_nop 0
	s_waitcnt lgkmcnt(9)
	v_mfma_f32_16x16x32_bf16 v[98:101], v[98:101], v[196:199], 0
	s_nop 0
	s_waitcnt lgkmcnt(8)
	v_mfma_f32_16x16x32_bf16 v[94:97], v[94:97], v[200:203], v[98:101]
	s_nop 4
	s_nop 0
	s_waitcnt lgkmcnt(7)
	v_mfma_f32_16x16x32_bf16 v[98:101], v[90:93], v[204:207], v[102:105]
	s_nop 2
	s_nop 0
	s_waitcnt lgkmcnt(6)
	v_mfma_f32_16x16x32_bf16 v[98:101], v[86:89], v[208:211], v[98:101]
	s_nop 0
	s_waitcnt lgkmcnt(5)
	v_mfma_f32_16x16x32_bf16 v[98:101], v[82:85], v[212:215], v[98:101]
	s_nop 0
	s_waitcnt lgkmcnt(4)
	v_mfma_f32_16x16x32_bf16 v[98:101], v[78:81], v[216:219], v[98:101]
	ds_read_b128 v[188:191], v135
	ds_read_b128 v[192:195], v135 offset:64
	ds_read_b128 v[196:199], v135 offset:2304
	ds_read_b128 v[200:203], v135 offset:2368
	ds_read_b128 v[204:207], v135 offset:4608
	ds_read_b128 v[208:211], v135 offset:4672
	ds_read_b128 v[212:215], v135 offset:6912
	ds_read_b128 v[216:219], v135 offset:6976
	s_nop 0
	s_waitcnt lgkmcnt(11)
	v_mfma_f32_16x16x32_bf16 v[90:93], v[90:93], v[220:223], v[94:97]
	s_nop 2
	s_nop 0
	s_waitcnt lgkmcnt(10)
	v_mfma_f32_16x16x32_bf16 v[86:89], v[86:89], v[224:227], v[90:93]
	s_nop 2
	s_nop 0
	s_waitcnt lgkmcnt(9)
	v_mfma_f32_16x16x32_bf16 v[82:85], v[82:85], v[228:231], v[86:89]
	s_nop 2
	s_nop 0
	s_waitcnt lgkmcnt(8)
	v_mfma_f32_16x16x32_bf16 v[78:81], v[78:81], v[232:235], v[82:85]
	s_nop 7
	ds_write2_b32 v179, v98, v78 offset1:16
	ds_write2_b32 v179, v99, v79 offset0:68 offset1:84
	ds_write2_b32 v179, v100, v80 offset0:136 offset1:152
	ds_write2_b32 v179, v101, v81 offset0:204 offset1:220
	s_nop 0
	s_nop 0
	s_waitcnt lgkmcnt(11)
	v_mfma_f32_16x16x32_bf16 v[78:81], v[188:191], v[74:77], v[110:113]
	s_waitcnt lgkmcnt(10)
	v_mfma_f32_16x16x32_bf16 v[78:81], v[192:195], v[66:69], v[78:81]
	s_nop 0
	s_nop 6
	v_pk_mul_f32 v[112:113], v[158:159], v[80:81] op_sel_hi:[0,1]
	v_pk_mul_f32 v[110:111], v[158:159], v[78:79] op_sel_hi:[0,1]
	s_nop 0
	s_waitcnt lgkmcnt(9)
	v_mfma_f32_16x16x32_bf16 v[78:81], v[196:199], v[74:77], v[114:117]
	s_waitcnt lgkmcnt(8)
	v_mfma_f32_16x16x32_bf16 v[78:81], v[200:203], v[66:69], v[78:81]
	s_nop 0
	s_nop 6
	v_pk_mul_f32 v[116:117], v[158:159], v[80:81] op_sel_hi:[0,1]
	v_pk_mul_f32 v[114:115], v[158:159], v[78:79] op_sel_hi:[0,1]
	s_nop 0
	s_waitcnt lgkmcnt(7)
	v_mfma_f32_16x16x32_bf16 v[78:81], v[204:207], v[74:77], v[106:109]
	s_waitcnt lgkmcnt(6)
	v_mfma_f32_16x16x32_bf16 v[78:81], v[208:211], v[66:69], v[78:81]
	s_nop 7
	v_pk_mul_f32 v[108:109], v[158:159], v[80:81] op_sel_hi:[0,1]
	v_pk_mul_f32 v[106:107], v[158:159], v[78:79] op_sel_hi:[0,1]
	s_nop 0
	s_waitcnt lgkmcnt(5)
	v_mfma_f32_16x16x32_bf16 v[74:77], v[212:215], v[74:77], v[118:121]
	s_nop 0
	s_waitcnt lgkmcnt(4)
	v_mfma_f32_16x16x32_bf16 v[66:69], v[216:219], v[66:69], v[74:77]
	s_nop 7
	v_pk_mul_f32 v[102:103], v[158:159], v[66:67] op_sel_hi:[0,1]
	v_cvt_pk_bf16_f32 v66, v110, s0
	ds_write_b16 v177, v66
	v_cvt_pk_bf16_f32 v66, v111, s0
	ds_write_b16 v177, v66 offset:272
	v_cvt_pk_bf16_f32 v66, v112, s0
	ds_write_b16 v177, v66 offset:544
	v_cvt_pk_bf16_f32 v66, v113, s0
	ds_write_b16 v177, v66 offset:816
	v_cvt_pk_bf16_f32 v66, v114, s0
	ds_write_b16 v177, v66 offset:4352
	v_cvt_pk_bf16_f32 v66, v115, s0
	ds_write_b16 v177, v66 offset:4624
	v_cvt_pk_bf16_f32 v66, v116, s0
	ds_write_b16 v177, v66 offset:4896
	v_cvt_pk_bf16_f32 v66, v117, s0
	ds_write_b16 v177, v66 offset:5168
	v_cvt_pk_bf16_f32 v66, v106, s0
	ds_write_b16 v177, v66 offset:8704
	v_cvt_pk_bf16_f32 v66, v107, s0
	ds_write_b16 v177, v66 offset:8976
	v_cvt_pk_bf16_f32 v66, v108, s0
	ds_write_b16 v177, v66 offset:9248
	v_cvt_pk_bf16_f32 v66, v109, s0
	ds_write_b16 v177, v66 offset:9520
	v_cvt_pk_bf16_f32 v66, v102, s0
	v_pk_mul_f32 v[104:105], v[158:159], v[68:69] op_sel_hi:[0,1]
	ds_write_b16 v177, v66 offset:13056
	v_cvt_pk_bf16_f32 v66, v103, s0
	ds_write_b16 v177, v66 offset:13328
	v_cvt_pk_bf16_f32 v66, v104, s0
	ds_write_b16 v177, v66 offset:13600
	v_cvt_pk_bf16_f32 v66, v105, s0
	ds_write_b16 v177, v66 offset:13872
	s_waitcnt lgkmcnt(0)
	s_barrier
	s_cbranch_scc0 .LBB0_1219
	s_mov_b32 s23, s21
	s_branch .LBB0_1224
